# chunk-task staging index math: u/48 and r*48, r*784 with 24-bit multiplies instead of v_mul_hi_i32 / v_mul_lo_u32
# baseline (speedup 1.0000x reference)
.LBB0_666:
	s_or_b64 exec, exec, s[12:13]
	s_add_i32 s9, s58, s30
	s_cmpk_lt_i32 s9, 0x800
	s_cselect_b64 s[64:65], -1, 0
	s_cmpk_gt_i32 s9, 0x7ff
	s_cselect_b64 s[62:63], -1, 0
	v_and_b32_e32 v96, 64, v116
	s_and_b64 vcc, exec, s[62:63]
	s_cbranch_vccnz .LBB0_758
	v_mov_b32_e32 v4, v170
	s_movk_i32 s10, 0xc90
	s_nop 0
	v_cmp_gt_i32_e64 s[24:25], s10, v4
	s_and_saveexec_b64 s[12:13], s[24:25]
	s_cbranch_execz .LBB0_669
	v_mul_u32_u24_e32 v0, 0xaaab, v4
	v_lshrrev_b32_e32 v0, 21, v0
	v_mul_u32_u24_e32 v1, 48, v0
	v_sub_u32_e32 v1, v4, v1
	v_mul_u32_u24_e32 v0, s79, v0
	v_lshlrev_b32_e32 v1, 4, v1
	v_add_u32_e32 v0, 0, v0
	v_and_b32_e32 v2, 0xffffff00, v1
	v_and_b32_e32 v1, 0xf0, v1
	v_add3_u32 v0, v0, v2, v1
	ds_write_b128 v0, v[52:55]
.LBB0_669:
	s_or_b64 exec, exec, s[12:13]
	s_movk_i32 s10, 0xa90
	v_add_u32_e32 v11, 0x200, v4
	v_cmp_gt_i32_e64 s[22:23], s10, v4
	s_and_saveexec_b64 s[12:13], s[22:23]
	s_cbranch_execz .LBB0_671
	v_mul_u32_u24_e32 v0, 0xaaab, v11
	v_lshrrev_b32_e32 v0, 21, v0
	v_mul_u32_u24_e32 v1, 48, v0
	v_sub_u32_e32 v1, v11, v1
	v_mul_u32_u24_e32 v0, s79, v0
	v_lshlrev_b32_e32 v1, 4, v1
	v_add_u32_e32 v0, 0, v0
	v_and_b32_e32 v2, 0xffffff00, v1
	v_and_b32_e32 v1, 0xf0, v1
	v_add3_u32 v0, v0, v2, v1
	ds_write_b128 v0, v[48:51]
.LBB0_671:
	s_or_b64 exec, exec, s[12:13]
	s_movk_i32 s10, 0x890
	v_add_u32_e32 v9, 0x400, v4
	v_cmp_gt_i32_e64 s[20:21], s10, v4
	s_and_saveexec_b64 s[12:13], s[20:21]
	s_cbranch_execz .LBB0_673
	v_mul_u32_u24_e32 v0, 0xaaab, v9
	v_lshrrev_b32_e32 v0, 21, v0
	v_mul_u32_u24_e32 v1, 48, v0
	v_sub_u32_e32 v1, v9, v1
	v_mul_u32_u24_e32 v0, s79, v0
	v_lshlrev_b32_e32 v1, 4, v1
	v_add_u32_e32 v0, 0, v0
	v_and_b32_e32 v2, 0xffffff00, v1
	v_and_b32_e32 v1, 0xf0, v1
	v_add3_u32 v0, v0, v2, v1
	ds_write_b128 v0, v[60:63]
.LBB0_673:
	s_or_b64 exec, exec, s[12:13]
	s_movk_i32 s10, 0x690
	v_add_u32_e32 v8, 0x600, v4
	v_cmp_gt_i32_e64 s[18:19], s10, v4
	s_and_saveexec_b64 s[12:13], s[18:19]
	s_cbranch_execz .LBB0_675
	v_mul_u32_u24_e32 v0, 0xaaab, v8
	v_lshrrev_b32_e32 v0, 21, v0
	v_mul_u32_u24_e32 v1, 48, v0
	v_sub_u32_e32 v1, v8, v1
	v_mul_u32_u24_e32 v0, s79, v0
	v_lshlrev_b32_e32 v1, 4, v1
	v_add_u32_e32 v0, 0, v0
	v_and_b32_e32 v2, 0xffffff00, v1
	v_and_b32_e32 v1, 0xf0, v1
	v_add3_u32 v0, v0, v2, v1
	ds_write_b128 v0, v[56:59]
.LBB0_675:
	s_or_b64 exec, exec, s[12:13]
	s_movk_i32 s10, 0x490
	v_add_u32_e32 v7, 0x800, v4
	v_cmp_gt_i32_e64 s[16:17], s10, v4
	s_and_saveexec_b64 s[12:13], s[16:17]
	s_cbranch_execz .LBB0_677
	v_mul_u32_u24_e32 v0, 0xaaab, v7
	v_lshrrev_b32_e32 v0, 21, v0
	v_mul_u32_u24_e32 v1, 48, v0
	v_sub_u32_e32 v1, v7, v1
	v_mul_u32_u24_e32 v0, s79, v0
	v_lshlrev_b32_e32 v1, 4, v1
	v_add_u32_e32 v0, 0, v0
	v_and_b32_e32 v2, 0xffffff00, v1
	v_and_b32_e32 v1, 0xf0, v1
	v_add3_u32 v0, v0, v2, v1
	ds_write_b128 v0, v[68:71]
.LBB0_677:
	s_or_b64 exec, exec, s[12:13]
	s_movk_i32 s10, 0x290
	v_add_u32_e32 v6, 0xa00, v4
	v_cmp_gt_i32_e64 s[14:15], s10, v4
	s_and_saveexec_b64 s[12:13], s[14:15]
	s_cbranch_execz .LBB0_679
	v_mul_u32_u24_e32 v0, 0xaaab, v6
	v_lshrrev_b32_e32 v0, 21, v0
	v_mul_u32_u24_e32 v1, 48, v0
	v_sub_u32_e32 v1, v6, v1
	v_mul_u32_u24_e32 v0, s79, v0
	v_lshlrev_b32_e32 v1, 4, v1
	v_add_u32_e32 v0, 0, v0
	v_and_b32_e32 v2, 0xffffff00, v1
	v_and_b32_e32 v1, 0xf0, v1
	v_add3_u32 v0, v0, v2, v1
	ds_write_b128 v0, v[64:67]
.LBB0_679:
	s_or_b64 exec, exec, s[12:13]
	s_movk_i32 s10, 0x8f
	v_cmp_lt_i32_e64 s[26:27], s10, v4
	s_movk_i32 s10, 0x90
	v_add_u32_e32 v5, 0xc00, v4
	v_cmp_gt_i32_e64 s[12:13], s10, v4
	s_and_saveexec_b64 s[66:67], s[12:13]
	s_cbranch_execz .LBB0_681
	v_mul_u32_u24_e32 v0, 0xaaab, v5
	v_lshrrev_b32_e32 v0, 21, v0
	v_mul_u32_u24_e32 v1, 48, v0
	v_sub_u32_e32 v1, v5, v1
	v_mul_u32_u24_e32 v0, s79, v0
	v_lshlrev_b32_e32 v1, 4, v1
	v_add_u32_e32 v0, 0, v0
	v_and_b32_e32 v2, 0xffffff00, v1
	v_and_b32_e32 v1, 0xf0, v1
	v_add3_u32 v0, v0, v2, v1
	ds_write_b128 v0, v[74:77]

.LBB0_689:
	v_mul_u32_u24_e32 v0, 0xaaab, v4
	v_lshrrev_b32_e32 v2, 21, v0
	v_mul_u32_u24_e32 v0, 48, v2
	v_sub_u32_e32 v12, v4, v0
	s_mov_b64 s[4:5], s[74:75]
	v_ashrrev_i32_e32 v13, 4, v12
	s_mov_b64 s[24:25], 0
	s_and_saveexec_b64 s[74:75], s[26:27]
	s_xor_b64 s[26:27], exec, s[74:75]
	v_add_u32_e32 v2, s34, v2
	v_mov_b64_e32 v[0:1], s[48:49]
	v_mad_i64_i32 v[0:1], s[74:75], v2, s81, v[0:1]
	v_lshlrev_b32_e32 v78, 11, v13
	s_mov_b64 s[24:25], exec
	v_lshl_add_u64 v[0:1], v[0:1], 0, v[78:79]
	s_andn2_saveexec_b64 s[26:27], s[26:27]
	s_cbranch_execz .LBB0_695
	s_and_b64 vcc, exec, s[70:71]
	s_mov_b64 s[74:75], s[24:25]
	s_cbranch_vccz .LBB0_694
	v_ashrrev_i32_e32 v3, 31, v2
	v_lshl_add_u64 v[0:1], v[2:3], 0, s[68:69]
	v_mov_b64_e32 v[2:3], s[4:5]
	v_mad_u64_u32 v[2:3], s[74:75], v0, s81, v[2:3]
	v_lshlrev_b32_e32 v0, 10, v13
	v_mad_i32_i24 v3, v1, s81, v3
	v_ashrrev_i32_e32 v1, 31, v0
	v_lshl_add_u64 v[0:1], v[0:1], 1, v[2:3]
	s_or_b64 s[74:75], s[24:25], exec

.LBB0_698:
	v_mul_u32_u24_e32 v0, 0xaaab, v11
	v_lshrrev_b32_e32 v2, 21, v0
	v_mul_u32_u24_e32 v0, 48, v2
	v_sub_u32_e32 v11, v11, v0
	s_movk_i32 s22, 0xfe8f
	v_ashrrev_i32_e32 v12, 4, v11
	v_cmp_lt_i32_e32 vcc, s22, v4
	s_mov_b64 s[22:23], 0
	s_and_saveexec_b64 s[26:27], vcc
	s_xor_b64 s[26:27], exec, s[26:27]
	v_add_u32_e32 v2, s34, v2
	v_mov_b64_e32 v[0:1], s[48:49]
	v_mad_i64_i32 v[0:1], s[72:73], v2, s81, v[0:1]
	v_lshlrev_b32_e32 v78, 11, v12
	s_mov_b64 s[22:23], exec
	v_lshl_add_u64 v[0:1], v[0:1], 0, v[78:79]
	s_andn2_saveexec_b64 s[26:27], s[26:27]
	s_cbranch_execz .LBB0_704
	s_and_b64 vcc, exec, s[70:71]
	s_mov_b64 s[72:73], s[22:23]
	s_cbranch_vccz .LBB0_703
	v_ashrrev_i32_e32 v3, 31, v2
	v_lshl_add_u64 v[0:1], v[2:3], 0, s[68:69]
	v_mov_b64_e32 v[2:3], s[74:75]
	v_mad_u64_u32 v[2:3], s[72:73], v0, s81, v[2:3]
	v_lshlrev_b32_e32 v0, 10, v12
	v_mad_i32_i24 v3, v1, s81, v3
	v_ashrrev_i32_e32 v1, 31, v0
	v_lshl_add_u64 v[0:1], v[0:1], 1, v[2:3]
	s_or_b64 s[72:73], s[22:23], exec

.LBB0_707:
	v_mul_u32_u24_e32 v0, 0xaaab, v9
	v_lshrrev_b32_e32 v2, 21, v0
	v_mul_u32_u24_e32 v0, 48, v2
	v_sub_u32_e32 v9, v9, v0
	s_movk_i32 s20, 0xfc8f
	v_ashrrev_i32_e32 v11, 4, v9
	v_cmp_lt_i32_e32 vcc, s20, v4
	s_mov_b64 s[20:21], 0
	s_and_saveexec_b64 s[24:25], vcc
	s_xor_b64 s[24:25], exec, s[24:25]
	v_add_u32_e32 v2, s34, v2
	v_mov_b64_e32 v[0:1], s[48:49]
	v_mad_i64_i32 v[0:1], s[26:27], v2, s81, v[0:1]
	v_lshlrev_b32_e32 v78, 11, v11
	s_mov_b64 s[20:21], exec
	v_lshl_add_u64 v[0:1], v[0:1], 0, v[78:79]
	s_andn2_saveexec_b64 s[24:25], s[24:25]
	s_cbranch_execz .LBB0_713
	s_and_b64 vcc, exec, s[70:71]
	s_mov_b64 s[26:27], s[20:21]
	s_cbranch_vccz .LBB0_712
	v_ashrrev_i32_e32 v3, 31, v2
	v_lshl_add_u64 v[0:1], v[2:3], 0, s[68:69]
	v_mov_b64_e32 v[2:3], s[74:75]
	v_mad_u64_u32 v[2:3], s[26:27], v0, s81, v[2:3]
	v_lshlrev_b32_e32 v0, 10, v11
	v_mad_i32_i24 v3, v1, s81, v3
	v_ashrrev_i32_e32 v1, 31, v0
	v_lshl_add_u64 v[0:1], v[0:1], 1, v[2:3]
	s_or_b64 s[26:27], s[20:21], exec

.LBB0_716:
	v_mul_u32_u24_e32 v0, 0xaaab, v8
	v_lshrrev_b32_e32 v2, 21, v0
	v_mul_u32_u24_e32 v0, 48, v2
	v_sub_u32_e32 v8, v8, v0
	s_movk_i32 s18, 0xfa8f
	v_ashrrev_i32_e32 v9, 4, v8
	v_cmp_lt_i32_e32 vcc, s18, v4
	s_mov_b64 s[18:19], 0
	s_and_saveexec_b64 s[22:23], vcc
	s_xor_b64 s[22:23], exec, s[22:23]
	v_add_u32_e32 v2, s34, v2
	v_mov_b64_e32 v[0:1], s[48:49]
	v_mad_i64_i32 v[0:1], s[24:25], v2, s81, v[0:1]
	v_lshlrev_b32_e32 v78, 11, v9
	s_mov_b64 s[18:19], exec
	v_lshl_add_u64 v[0:1], v[0:1], 0, v[78:79]
	s_andn2_saveexec_b64 s[22:23], s[22:23]
	s_cbranch_execz .LBB0_722
	s_and_b64 vcc, exec, s[70:71]
	s_mov_b64 s[24:25], s[18:19]
	s_cbranch_vccz .LBB0_721
	v_ashrrev_i32_e32 v3, 31, v2
	v_lshl_add_u64 v[0:1], v[2:3], 0, s[68:69]
	v_mov_b64_e32 v[2:3], s[74:75]
	v_mad_u64_u32 v[2:3], s[24:25], v0, s81, v[2:3]
	v_lshlrev_b32_e32 v0, 10, v9
	v_mad_i32_i24 v3, v1, s81, v3
	v_ashrrev_i32_e32 v1, 31, v0
	v_lshl_add_u64 v[0:1], v[0:1], 1, v[2:3]
	s_or_b64 s[24:25], s[18:19], exec

.LBB0_725:
	v_mul_u32_u24_e32 v0, 0xaaab, v7
	v_lshrrev_b32_e32 v2, 21, v0
	v_mul_u32_u24_e32 v0, 48, v2
	v_sub_u32_e32 v7, v7, v0
	s_movk_i32 s16, 0xf88f
	v_ashrrev_i32_e32 v8, 4, v7
	v_cmp_lt_i32_e32 vcc, s16, v4
	s_mov_b64 s[16:17], 0
	s_and_saveexec_b64 s[20:21], vcc
	s_xor_b64 s[20:21], exec, s[20:21]
	v_add_u32_e32 v2, s34, v2
	v_mov_b64_e32 v[0:1], s[48:49]
	v_mad_i64_i32 v[0:1], s[22:23], v2, s81, v[0:1]
	v_lshlrev_b32_e32 v78, 11, v8
	s_mov_b64 s[16:17], exec
	v_lshl_add_u64 v[0:1], v[0:1], 0, v[78:79]
	s_andn2_saveexec_b64 s[20:21], s[20:21]
	s_cbranch_execz .LBB0_731
	s_and_b64 vcc, exec, s[70:71]
	s_mov_b64 s[22:23], s[16:17]
	s_cbranch_vccz .LBB0_730
	v_ashrrev_i32_e32 v3, 31, v2
	v_lshl_add_u64 v[0:1], v[2:3], 0, s[68:69]
	v_mov_b64_e32 v[2:3], s[74:75]
	v_mad_u64_u32 v[2:3], s[22:23], v0, s81, v[2:3]
	v_lshlrev_b32_e32 v0, 10, v8
	v_mad_i32_i24 v3, v1, s81, v3
	v_ashrrev_i32_e32 v1, 31, v0
	v_lshl_add_u64 v[0:1], v[0:1], 1, v[2:3]
	s_or_b64 s[22:23], s[16:17], exec

.LBB0_734:
	v_mul_u32_u24_e32 v0, 0xaaab, v6
	v_lshrrev_b32_e32 v2, 21, v0
	v_mul_u32_u24_e32 v0, 48, v2
	v_sub_u32_e32 v6, v6, v0
	s_movk_i32 s14, 0xf68f
	v_ashrrev_i32_e32 v7, 4, v6
	v_cmp_lt_i32_e32 vcc, s14, v4
	s_mov_b64 s[14:15], 0
	s_and_saveexec_b64 s[18:19], vcc
	s_xor_b64 s[18:19], exec, s[18:19]
	v_add_u32_e32 v2, s34, v2
	v_mov_b64_e32 v[0:1], s[48:49]
	v_mad_i64_i32 v[0:1], s[20:21], v2, s81, v[0:1]
	v_lshlrev_b32_e32 v78, 11, v7
	s_mov_b64 s[14:15], exec
	v_lshl_add_u64 v[0:1], v[0:1], 0, v[78:79]
	s_andn2_saveexec_b64 s[18:19], s[18:19]
	s_cbranch_execz .LBB0_740
	s_and_b64 vcc, exec, s[70:71]
	s_mov_b64 s[20:21], s[14:15]
	s_cbranch_vccz .LBB0_739
	v_ashrrev_i32_e32 v3, 31, v2
	v_lshl_add_u64 v[0:1], v[2:3], 0, s[68:69]
	v_mov_b64_e32 v[2:3], s[74:75]
	v_mad_u64_u32 v[2:3], s[20:21], v0, s81, v[2:3]
	v_lshlrev_b32_e32 v0, 10, v7
	v_mad_i32_i24 v3, v1, s81, v3
	v_ashrrev_i32_e32 v1, 31, v0
	v_lshl_add_u64 v[0:1], v[0:1], 1, v[2:3]
	s_or_b64 s[20:21], s[14:15], exec

.LBB0_743:
	v_mul_u32_u24_e32 v0, 0xaaab, v5
	v_lshrrev_b32_e32 v2, 21, v0
	v_mul_u32_u24_e32 v0, 48, v2
	v_sub_u32_e32 v5, v5, v0
	s_movk_i32 s12, 0xf48f
	v_ashrrev_i32_e32 v6, 4, v5
	v_cmp_lt_i32_e32 vcc, s12, v4
	s_mov_b64 s[12:13], 0
	s_and_saveexec_b64 s[16:17], vcc
	s_xor_b64 s[16:17], exec, s[16:17]
	v_add_u32_e32 v2, s34, v2
	v_mov_b64_e32 v[0:1], s[48:49]
	v_mad_i64_i32 v[0:1], s[18:19], v2, s81, v[0:1]
	v_lshlrev_b32_e32 v78, 11, v6
	s_mov_b64 s[12:13], exec
	v_lshl_add_u64 v[0:1], v[0:1], 0, v[78:79]
	s_andn2_saveexec_b64 s[16:17], s[16:17]
	s_cbranch_execz .LBB0_749
	s_and_b64 vcc, exec, s[70:71]
	s_mov_b64 s[18:19], s[12:13]
	s_cbranch_vccz .LBB0_748
	v_ashrrev_i32_e32 v3, 31, v2
	v_lshl_add_u64 v[0:1], v[2:3], 0, s[68:69]
	v_mov_b64_e32 v[2:3], s[74:75]
	v_mad_u64_u32 v[2:3], s[18:19], v0, s81, v[2:3]
	v_lshlrev_b32_e32 v0, 10, v6
	v_mad_i32_i24 v3, v1, s81, v3
	v_ashrrev_i32_e32 v1, 31, v0
	v_lshl_add_u64 v[0:1], v[0:1], 1, v[2:3]
	s_or_b64 s[18:19], s[12:13], exec
